# RAW side-buffer rows stored write-through (sc1); panel barrier after the up phase no longer writes the whole L2 back when the panel shares one XCD
# speedup vs baseline: 1.0129x; 1.0050x over previous
.LBB0_320:
	s_or_b64 exec, exec, s[0:1]
	s_lshl_b32 s0, s69, 2
	v_readlane_b32 s2, v253, 22
	s_add_i32 s4, s0, s2
	v_readlane_b32 s3, v253, 23
	s_cmp_lt_i32 s4, 22
	s_cselect_b64 s[2:3], -1, 0
	s_and_b64 s[0:1], s[2:3], exec
	v_readlane_b32 s0, v253, 25
	s_cselect_b32 s68, s4, s68
	v_readlane_b32 s1, v253, 26
	s_cselect_b32 s54, s0, s54
	s_and_b64 s[4:5], s[28:29], vcc
	v_ashrrev_i32_e32 v187, 31, v186
	s_lshl_b32 s6, s68, 7
	s_ashr_i32 s7, s6, 31
	s_lshl_b64 s[6:7], s[6:7], 2
	s_add_u32 s6, s30, s6
	s_addc_u32 s7, s31, s7
	v_lshl_add_u64 v[138:139], v[186:187], 2, s[6:7]
	s_mov_b64 s[0:1], 0x2c00
	v_add_co_u32_e32 v136, vcc, 0x2000, v138
	v_lshl_add_u64 v[134:135], v[138:139], 0, s[0:1]
	s_nop 0
	v_addc_co_u32_e32 v137, vcc, 0, v139, vcc
	s_mov_b64 s[0:1], 0x5800
	global_load_dwordx4 v[130:133], v[138:139], off offset:16
	global_load_dwordx4 v[142:145], v[138:139], off
	v_lshl_add_u64 v[140:141], v[138:139], 0, s[0:1]
	v_add_co_u32_e32 v138, vcc, 0x5000, v138
	global_load_dwordx4 v[146:149], v[136:137], off offset:3072
	s_nop 0
	global_load_dwordx4 v[134:137], v[134:135], off offset:16
	v_addc_co_u32_e32 v139, vcc, 0, v139, vcc
	global_load_dwordx4 v[150:153], v[138:139], off offset:2048
	s_nop 0
	global_load_dwordx4 v[138:141], v[140:141], off offset:16
	s_and_saveexec_b64 s[0:1], s[4:5]
	s_cbranch_execz .LBB0_322
	s_ashr_i32 s55, s54, 31
	v_add_u32_e32 v0, -14, v184
	v_lshl_add_u64 v[154:155], s[54:55], 1, v[0:1]
	v_mov_b64_e32 v[156:157], s[48:49]
	s_movk_i32 s6, 0x2c00
	v_mad_u64_u32 v[156:157], s[4:5], v154, s6, v[156:157]
	s_lshl_b32 s4, s68, 7
	v_mad_i32_i24 v157, v155, s6, v157
	s_ashr_i32 s5, s4, 31
	v_lshl_add_u64 v[154:155], s[4:5], 2, v[156:157]
	v_lshl_add_u64 v[154:155], v[186:187], 2, v[154:155]
	global_store_dwordx4 v[154:155], v[38:41], off sc1
	global_store_dwordx4 v[154:155], v[34:37], off offset:16 sc1
.LBB0_322:
	s_or_b64 exec, exec, s[0:1]
	v_cmp_lt_i32_e32 vcc, 1, v184
	s_xor_b64 s[0:1], s[36:37], -1
	s_or_b64 s[0:1], s[0:1], vcc
	s_and_saveexec_b64 s[4:5], s[0:1]
	s_xor_b64 s[0:1], exec, s[4:5]
	s_lshl_b32 s4, s68, 7
	s_ashr_i32 s5, s4, 31
	v_mov_b64_e32 v[182:183], s[4:5]
	s_andn2_saveexec_b64 s[0:1], s[0:1]
	s_cbranch_execz .LBB0_326
	s_ashr_i32 s55, s54, 31
	v_ashrrev_i32_e32 v185, 31, v184
	v_lshl_add_u64 v[154:155], s[54:55], 1, v[184:185]
	v_mov_b64_e32 v[156:157], s[10:11]
	s_movk_i32 s6, 0x5800
	v_mad_u64_u32 v[156:157], s[4:5], v154, s6, v[156:157]
	s_lshl_b32 s4, s68, 7
	v_mad_i32_i24 v157, v155, s6, v157
	s_ashr_i32 s5, s4, 31
	v_lshl_add_u64 v[154:155], s[4:5], 2, v[156:157]
	v_lshl_add_u64 v[154:155], v[186:187], 2, v[154:155]
	global_store_dwordx4 v[154:155], v[126:129], off sc1
	global_store_dwordx4 v[154:155], v[122:125], off offset:16 sc1
	v_add_co_u32_e32 v154, vcc, 0x2000, v154
	v_mov_b64_e32 v[182:183], s[4:5]
	s_nop 0
	v_addc_co_u32_e32 v155, vcc, 0, v155, vcc
	global_store_dwordx4 v[154:155], v[94:97], off offset:3072 sc1
	global_store_dwordx4 v[154:155], v[90:93], off offset:3088 sc1

.LBB0_1131:
	v_readlane_b32 s0, v253, 27
	v_readlane_b32 s1, v253, 28
	s_and_b64 vcc, exec, s[0:1]
	s_cbranch_vccz .LBB0_1137
	s_xor_b64 s[2:3], s[84:85], -1
	s_mov_b64 s[0:1], -1
	s_and_b64 vcc, exec, s[2:3]
	s_cbranch_vccz .LBB0_1161
	s_waitcnt vmcnt(0)
	v_readlane_b32 s0, v252, 36
	s_add_i32 s26, s0, 1
	s_waitcnt vmcnt(0) lgkmcnt(0)
	s_barrier
	s_mov_b64 s[0:1], exec
	v_readlane_b32 s2, v251, 5
	v_readlane_b32 s3, v251, 6
	s_and_b64 s[2:3], s[0:1], s[2:3]
	s_mov_b64 exec, s[2:3]
	s_cbranch_execz .LBB0_1160
	s_add_i32 s2, s18, -1
	s_mul_hi_i32 s3, s2, 0x38e38e39
	s_lshr_b32 s4, s3, 31
	s_ashr_i32 s3, s3, 1
	s_add_i32 s3, s3, s4
	s_mul_i32 s3, s3, 9
	s_sub_i32 s2, s2, s3
	s_cmp_lg_u32 s2, 99
	v_readlane_b32 s4, v252, 43
	s_cselect_b64 s[2:3], -1, 0
	v_readlane_b32 s5, v252, 44
	s_and_b64 s[2:3], s[4:5], s[2:3]
	s_and_b64 vcc, exec, s[2:3]
	s_cbranch_vccnz .LBB0_1136
	buffer_wbl2 sc1
	s_waitcnt vmcnt(0)
